# lever 1 counted waits: attention-A S-MFMA section waits per K fragment (lgkmcnt 3/2/3/2) instead of draining all four K reads before the first S MFMA
# baseline (speedup 1.0000x reference)
; #define FLAS __attribute__((address_space(3)))
; #define FA_SB() __builtin_amdgcn_sched_barrier(0)
; #define FA_EXP2(J, PX, R) do { const float e0_ = __builtin_amdgcn_exp2f(PX[R]), e1_ = __builtin_amdgcn_exp2f(PX[(R) + 1]); ps += e0_; ps += e1_; PWN[(J) >> 2][(J) & 3] = cvtpk(e0_, e1_); } while (0)
; __device__ __forceinline__ void attn_unit_a(FLAS unsigned char* lds, const Unit u) {
;     ...
;         if (ziN) { pN0 = __builtin_amdgcn_mfma_f32_32x32x16_bf16(kf[0], qr[0], z16, 0, 0, 0); FA_EXP2(8, pC1, 0); FA_SB(); pN1 = __builtin_amdgcn_mfma_f32_32x32x16_bf16(kf[1], qr[0], z16, 0, 0, 0); }
;         else { pN0 = __builtin_amdgcn_mfma_f32_32x32x16_bf16(kf[0], qr[0], pN0, 0, 0, 0); FA_EXP2(8, pC1, 0); FA_SB(); pN1 = __builtin_amdgcn_mfma_f32_32x32x16_bf16(kf[1], qr[0], pN1, 0, 0, 0); }
;         kf[0] = FA_KF(2, 0); kf[1] = FA_KF(2, 1); FA_EXP2(9, pC1, 2); FA_SB();
;         pN0 = __builtin_amdgcn_mfma_f32_32x32x16_bf16(kf[2], qr[1], pN0, 0, 0, 0); FA_EXP2(10, pC1, 4); FA_SB();
;         pN1 = __builtin_amdgcn_mfma_f32_32x32x16_bf16(kf[3], qr[1], pN1, 0, 0, 0); kf[2] = FA_KF(3, 0); kf[3] = FA_KF(3, 1); FA_EXP2(11, pC1, 6); FA_SB();
;         pN0 = __builtin_amdgcn_mfma_f32_32x32x16_bf16(kf[0], qr[2], pN0, 0, 0, 0); FA_EXP2(12, pC1, 8); FA_SB();
;         pN1 = __builtin_amdgcn_mfma_f32_32x32x16_bf16(kf[1], qr[2], pN1, 0, 0, 0); FA_EXP2(13, pC1, 10); FA_SB();
;         pN0 = __builtin_amdgcn_mfma_f32_32x32x16_bf16(kf[2], qr[3], pN0, 0, 0, 0); FA_EXP2(14, pC1, 12); FA_SB();
;         pN1 = __builtin_amdgcn_mfma_f32_32x32x16_bf16(kf[3], qr[3], pN1, 0, 0, 0); FA_EXP2(15, pC1, 14); FA_SB();
;     ...
;         lsum += ps; cbC = cbN;
;         if (i + 2 < NT) { *(FLAS u32x4*)(lds + LA_K + (i & 1) * KBUF + kdst) = kreg;
; #pragma unroll
;             for (int j = 0; j < 2; ++j) { *(FLAS u32x2*)(lds + LA_V + ((i + 2) & 3) * VBUF + vdst + j * 64 * VPITCH) = (u32x2){vreg[j].x, vreg[j].y}; *(FLAS u32x2*)(lds + LA_V + ((i + 2) & 3) * VBUF + vdst + j * 64 * VPITCH + 16) = (u32x2){vreg[j].z, vreg[j].w}; } }
.Lz_go_e:
	s_waitcnt lgkmcnt(3)
	v_mfma_f32_32x32x16_bf16 v[64:79], v[204:207], v[160:163], v[144:159]
	v_exp_f32_e32 v112, v112
	v_exp_f32_e32 v113, v113
	v_add_f32_e32 v212, v110, v212
	v_add_f32_e32 v212, v111, v212
	s_waitcnt lgkmcnt(2)
	v_mfma_f32_32x32x16_bf16 v[80:95], v[200:203], v[160:163], v[144:159]
	v_exp_f32_e32 v114, v114
	v_exp_f32_e32 v115, v115
.Lk2_e:
	ds_read_b128 v[128:131], v249 offset:8192
	ds_read_b128 v[132:135], v249 offset:8704
	s_add_i32 s34, s19, 2
	s_waitcnt lgkmcnt(3)
	v_mfma_f32_32x32x16_bf16 v[64:79], v[196:199], v[164:167], v[64:79]
	v_exp_f32_e32 v116, v116
	v_exp_f32_e32 v117, v117
	s_waitcnt lgkmcnt(2)
	v_mfma_f32_32x32x16_bf16 v[80:95], v[192:195], v[164:167], v[80:95]
	ds_read_b128 v[136:139], v250 offset:8192
	ds_read_b128 v[140:143], v250 offset:8704
	s_and_b32 s0, s34, 2
	s_mulk_i32 s0, 0x4800
	v_add_u32_e32 v188, s0, v245
	v_add_u32_e32 v189, 0x4000, v188
	v_add_u32_e32 v188, 0x6000, v188
	s_waitcnt vmcnt(2)
	ds_write_b128 v225, v[176:179]
	s_waitcnt vmcnt(1)
	ds_write2_b64 v189, v[180:181], v[182:183] offset1:2
	s_waitcnt vmcnt(0)
	ds_write2_b64 v188, v[184:185], v[186:187] offset0:128 offset1:130
	v_exp_f32_e32 v118, v118
	v_exp_f32_e32 v119, v119
	s_and_b32 s0, s19, 2
	s_mulk_i32 s0, 0x4800
	v_add_u32_e32 v201, s0, v251
	s_waitcnt lgkmcnt(5)
	v_mfma_f32_32x32x16_bf16 v[64:79], v[128:131], v[168:171], v[64:79]
	ds_read_b128 v[128:131], v201 offset:16384
	v_exp_f32_e32 v120, v120
	v_exp_f32_e32 v121, v121
	v_mfma_f32_32x32x16_bf16 v[80:95], v[132:135], v[168:171], v[80:95]
	ds_read_b128 v[132:135], v201 offset:20992
	v_exp_f32_e32 v122, v122
	v_exp_f32_e32 v123, v123
	s_waitcnt lgkmcnt(5)
	v_mfma_f32_32x32x16_bf16 v[64:79], v[136:139], v[172:175], v[64:79]
	ds_read_b128 v[136:139], v201 offset:25600
	v_exp_f32_e32 v124, v124
	v_exp_f32_e32 v125, v125
	v_mfma_f32_32x32x16_bf16 v[80:95], v[140:143], v[172:175], v[80:95]
	v_exp_f32_e32 v126, v126
	v_exp_f32_e32 v127, v127
	v_cvt_pk_bf16_f32 v140, v96, v97
	v_cvt_pk_bf16_f32 v141, v98, v99
	v_cvt_pk_bf16_f32 v142, v100, v101
	v_cvt_pk_bf16_f32 v143, v102, v103

; #define FLAS __attribute__((address_space(3)))
; #define FA_SB() __builtin_amdgcn_sched_barrier(0)
; #define FA_EXP2(J, PX, R) do { const float e0_ = __builtin_amdgcn_exp2f(PX[R]), e1_ = __builtin_amdgcn_exp2f(PX[(R) + 1]); ps += e0_; ps += e1_; PWN[(J) >> 2][(J) & 3] = cvtpk(e0_, e1_); } while (0)
; __device__ __forceinline__ void attn_unit_a(FLAS unsigned char* lds, const Unit u) {
;     ...
;         if (ziN) { pN0 = __builtin_amdgcn_mfma_f32_32x32x16_bf16(kf[0], qr[0], z16, 0, 0, 0); FA_EXP2(8, pC1, 0); FA_SB(); pN1 = __builtin_amdgcn_mfma_f32_32x32x16_bf16(kf[1], qr[0], z16, 0, 0, 0); }
;         else { pN0 = __builtin_amdgcn_mfma_f32_32x32x16_bf16(kf[0], qr[0], pN0, 0, 0, 0); FA_EXP2(8, pC1, 0); FA_SB(); pN1 = __builtin_amdgcn_mfma_f32_32x32x16_bf16(kf[1], qr[0], pN1, 0, 0, 0); }
;         kf[0] = FA_KF(2, 0); kf[1] = FA_KF(2, 1); FA_EXP2(9, pC1, 2); FA_SB();
;         pN0 = __builtin_amdgcn_mfma_f32_32x32x16_bf16(kf[2], qr[1], pN0, 0, 0, 0); FA_EXP2(10, pC1, 4); FA_SB();
;         pN1 = __builtin_amdgcn_mfma_f32_32x32x16_bf16(kf[3], qr[1], pN1, 0, 0, 0); kf[2] = FA_KF(3, 0); kf[3] = FA_KF(3, 1); FA_EXP2(11, pC1, 6); FA_SB();
;         pN0 = __builtin_amdgcn_mfma_f32_32x32x16_bf16(kf[0], qr[2], pN0, 0, 0, 0); FA_EXP2(12, pC1, 8); FA_SB();
;         pN1 = __builtin_amdgcn_mfma_f32_32x32x16_bf16(kf[1], qr[2], pN1, 0, 0, 0); FA_EXP2(13, pC1, 10); FA_SB();
;         pN0 = __builtin_amdgcn_mfma_f32_32x32x16_bf16(kf[2], qr[3], pN0, 0, 0, 0); FA_EXP2(14, pC1, 12); FA_SB();
;         pN1 = __builtin_amdgcn_mfma_f32_32x32x16_bf16(kf[3], qr[3], pN1, 0, 0, 0); FA_EXP2(15, pC1, 14); FA_SB();
;     ...
;         lsum += ps; cbC = cbN;
;         if (i + 2 < NT) { *(FLAS u32x4*)(lds + LA_K + (i & 1) * KBUF + kdst) = kreg;
; #pragma unroll
;             for (int j = 0; j < 2; ++j) { *(FLAS u32x2*)(lds + LA_V + ((i + 2) & 3) * VBUF + vdst + j * 64 * VPITCH) = (u32x2){vreg[j].x, vreg[j].y}; *(FLAS u32x2*)(lds + LA_V + ((i + 2) & 3) * VBUF + vdst + j * 64 * VPITCH + 16) = (u32x2){vreg[j].z, vreg[j].w}; } }
.Lz_go_o:
	s_waitcnt lgkmcnt(3)
	v_mfma_f32_32x32x16_bf16 v[96:111], v[200:203], v[160:163], v[144:159]
	v_exp_f32_e32 v80, v80
	v_exp_f32_e32 v81, v81
	v_add_f32_e32 v212, v78, v212
	v_add_f32_e32 v212, v79, v212
	s_waitcnt lgkmcnt(2)
	v_mfma_f32_32x32x16_bf16 v[112:127], v[196:199], v[160:163], v[144:159]
	v_exp_f32_e32 v82, v82
	v_exp_f32_e32 v83, v83
.Lk2_o:
	ds_read_b128 v[128:131], v249
	ds_read_b128 v[132:135], v249 offset:512
	s_waitcnt lgkmcnt(3)
	v_mfma_f32_32x32x16_bf16 v[96:111], v[192:195], v[164:167], v[96:111]
	v_exp_f32_e32 v84, v84
	v_exp_f32_e32 v85, v85
	s_waitcnt lgkmcnt(2)
	v_mfma_f32_32x32x16_bf16 v[112:127], v[188:191], v[164:167], v[112:127]
	ds_read_b128 v[136:139], v250
	ds_read_b128 v[140:143], v250 offset:512
	v_add_u32_e32 v204, s18, v245
	v_add_u32_e32 v205, 0x4000, v204
	v_add_u32_e32 v204, 0x6000, v204
	s_waitcnt vmcnt(2)
	ds_write_b128 v225, v[176:179] offset:8192
	s_waitcnt vmcnt(1)
	ds_write2_b64 v205, v[180:181], v[182:183] offset1:2
	s_waitcnt vmcnt(0)
	ds_write2_b64 v204, v[184:185], v[186:187] offset0:128 offset1:130
	v_exp_f32_e32 v86, v86
	v_exp_f32_e32 v87, v87
	s_add_i32 s12, s34, -1
	s_and_b32 s18, s12, 3
	s_mulk_i32 s18, 0x4800
	v_add_u32_e32 v200, s18, v251
	s_waitcnt lgkmcnt(5)
	v_mfma_f32_32x32x16_bf16 v[96:111], v[128:131], v[168:171], v[96:111]
	ds_read_b128 v[128:131], v200 offset:16384
	v_exp_f32_e32 v88, v88
	v_exp_f32_e32 v89, v89
	v_mfma_f32_32x32x16_bf16 v[112:127], v[132:135], v[168:171], v[112:127]
	ds_read_b128 v[132:135], v200 offset:20992
	v_exp_f32_e32 v90, v90
	v_exp_f32_e32 v91, v91
	s_waitcnt lgkmcnt(5)
	v_mfma_f32_32x32x16_bf16 v[96:111], v[136:139], v[172:175], v[96:111]
	ds_read_b128 v[136:139], v200 offset:25600
	v_exp_f32_e32 v92, v92
	v_exp_f32_e32 v93, v93
	v_mfma_f32_32x32x16_bf16 v[112:127], v[140:143], v[172:175], v[112:127]
	v_exp_f32_e32 v94, v94
	v_exp_f32_e32 v95, v95
